# a_in: the two MFMA groups per trip with rotated accumulators are issued as forward accumulate chains too
# speedup vs baseline: 1.0056x; 1.0006x over previous
.LBB0_254:
	s_ashr_i32 s61, s60, 31
	s_lshl_b64 s[62:63], s[60:61], 19
	s_add_u32 s62, s35, s62
	s_addc_u32 s63, s47, s63
	s_and_b64 s[64:65], s[12:13], exec
	s_cselect_b32 s3, s63, s69
	s_cselect_b32 s61, s62, s68
	s_ashr_i32 s59, s58, 31
	s_lshl_b64 s[64:65], s[58:59], 19
	s_add_u32 s64, s49, s64
	s_addc_u32 s65, s70, s65
	s_and_b64 s[92:93], s[12:13], exec
	s_cselect_b32 s91, s65, s67
	s_cselect_b32 s92, s64, s66
	s_lshl_b32 s59, s14, 8
	v_add_u32_e32 v0, s59, v182
	s_add_u32 s93, s66, 0x100
	s_waitcnt lgkmcnt(0)
	v_ashrrev_i32_e32 v1, 31, v0
	s_addc_u32 s94, s67, 0
	v_lshl_add_u64 v[72:73], v[0:1], 4, s[26:27]
	s_add_u32 s14, s68, 0x40080
	s_addc_u32 s15, s69, 0
	s_mov_b32 s95, -2
	s_mov_b64 s[66:67], 0
	s_cmp_eq_u32 s90, 1
	s_cbranch_scc1 .Lfa_2
	v_add_u32_e32 v74, s83, v181
	ds_read_b128 v[88:91], v74
	v_xor_b32_e32 v253, 64, v74
	ds_read_b128 v[108:111], v253
	ds_read_b128 v[128:131], v74 offset:2048
	ds_read_b128 v[144:147], v253 offset:2048
	v_add_u32_e32 v74, s84, v181
	ds_read_b128 v[148:151], v74
	v_xor_b32_e32 v253, 64, v74
	ds_read_b128 v[152:155], v253
	ds_read_b128 v[176:179], v74 offset:2048
	ds_read_b128 v[190:193], v253 offset:2048
	s_add_u32 s68, s14, 0xfffc0080
	s_addc_u32 s69, s15, -1
	s_and_b64 s[66:67], s[66:67], exec
	s_cselect_b32 s69, s3, s69
	s_cselect_b32 s68, s61, s68
	s_cselect_b32 s67, s91, s94
	s_cselect_b32 s66, s92, s93
	v_lshl_add_u64 v[74:75], s[14:15], 0, v[170:171]
	s_add_i32 m0, s74, 0xc000
	ds_read_b128 v[194:197], v187
	v_xor_b32_e32 v253, 64, v187
	ds_read_b128 v[198:201], v253
	ds_read_b128 v[202:205], v187 offset:2048
	ds_read_b128 v[206:209], v253 offset:2048
	ds_read_b128 v[210:213], v187 offset:4096
	ds_read_b128 v[214:217], v253 offset:4096
	ds_read_b128 v[218:221], v187 offset:6144
	ds_read_b128 v[222:225], v253 offset:6144
	global_load_lds_dwordx4 v[74:75], off
	v_lshl_add_u64 v[74:75], s[14:15], 0, v[168:169]
	s_add_i32 m0, s74, 0xe000
	s_nop 0
	global_load_lds_dwordx4 v[74:75], off
	s_waitcnt vmcnt(24)
	s_waitcnt lgkmcnt(0)
	s_setprio 1
	s_barrier
	v_mfma_f32_16x16x32_bf16 v[140:143], v[88:91], v[194:197], 0
	v_mfma_f32_16x16x32_bf16 v[136:139], v[128:131], v[194:197], 0
	v_mfma_f32_16x16x32_bf16 v[120:123], v[88:91], v[202:205], 0
	v_mfma_f32_16x16x32_bf16 v[116:119], v[128:131], v[202:205], 0
	v_mfma_f32_16x16x32_bf16 v[100:103], v[88:91], v[210:213], 0
	v_mfma_f32_16x16x32_bf16 v[96:99], v[128:131], v[210:213], 0
	v_mfma_f32_16x16x32_bf16 v[80:83], v[88:91], v[218:221], 0
	v_mfma_f32_16x16x32_bf16 v[74:77], v[128:131], v[218:221], 0
	v_mfma_f32_16x16x32_bf16 v[140:143], v[108:111], v[198:201], v[140:143]
	v_mfma_f32_16x16x32_bf16 v[136:139], v[144:147], v[198:201], v[136:139]
	v_mfma_f32_16x16x32_bf16 v[120:123], v[108:111], v[206:209], v[120:123]
	v_mfma_f32_16x16x32_bf16 v[116:119], v[144:147], v[206:209], v[116:119]
	v_mfma_f32_16x16x32_bf16 v[100:103], v[108:111], v[214:217], v[100:103]
	v_mfma_f32_16x16x32_bf16 v[96:99], v[144:147], v[214:217], v[96:99]
	v_mfma_f32_16x16x32_bf16 v[80:83], v[108:111], v[222:225], v[80:83]
	v_mfma_f32_16x16x32_bf16 v[74:77], v[144:147], v[222:225], v[74:77]
	s_setprio 0
	s_setprio 1
	v_mfma_f32_16x16x32_bf16 v[132:135], v[148:151], v[194:197], 0
	v_mfma_f32_16x16x32_bf16 v[132:135], v[152:155], v[198:201], v[132:135]
	v_mfma_f32_16x16x32_bf16 v[124:127], v[176:179], v[194:197], 0
	v_mfma_f32_16x16x32_bf16 v[124:127], v[190:193], v[198:201], v[124:127]
	v_mfma_f32_16x16x32_bf16 v[112:115], v[148:151], v[202:205], 0
	v_mfma_f32_16x16x32_bf16 v[112:115], v[152:155], v[206:209], v[112:115]
	v_mfma_f32_16x16x32_bf16 v[104:107], v[176:179], v[202:205], 0
	v_mfma_f32_16x16x32_bf16 v[104:107], v[190:193], v[206:209], v[104:107]
	v_mfma_f32_16x16x32_bf16 v[92:95], v[148:151], v[210:213], 0
	v_mfma_f32_16x16x32_bf16 v[92:95], v[152:155], v[214:217], v[92:95]
	v_mfma_f32_16x16x32_bf16 v[84:87], v[176:179], v[210:213], 0
	v_mfma_f32_16x16x32_bf16 v[84:87], v[190:193], v[214:217], v[84:87]
	v_mfma_f32_16x16x32_bf16 v[68:71], v[148:151], v[218:221], 0
	v_mfma_f32_16x16x32_bf16 v[68:71], v[152:155], v[222:225], v[68:71]
	v_mfma_f32_16x16x32_bf16 v[64:67], v[176:179], v[218:221], 0
	v_mfma_f32_16x16x32_bf16 v[64:67], v[190:193], v[222:225], v[64:67]
	s_barrier
	s_setprio 0
	s_add_i32 s96, s83, s71
	v_lshl_add_u64 v[226:227], s[66:67], 0, v[162:163]
	s_mov_b32 m0, s96
	ds_read_b128 v[194:197], v187 offset:16384
	v_xor_b32_e32 v253, 64, v187
	ds_read_b128 v[198:201], v253 offset:16384
	ds_read_b128 v[202:205], v187 offset:18432
	ds_read_b128 v[206:209], v253 offset:18432
	ds_read_b128 v[210:213], v187 offset:20480
	ds_read_b128 v[214:217], v253 offset:20480
	ds_read_b128 v[218:221], v187 offset:22528
	ds_read_b128 v[222:225], v253 offset:22528
	global_load_lds_dwordx4 v[226:227], off
	s_add_i32 m0, s96, 0x2000
	s_add_u32 s96, s66, 0x40000
	v_lshl_add_u64 v[228:229], s[66:67], 0, v[166:167]
	s_addc_u32 s97, s67, 0
	s_add_i32 vcc_lo, s84, s71
	global_load_lds_dwordx4 v[228:229], off
	v_lshl_add_u64 v[78:79], s[96:97], 0, v[162:163]
	s_mov_b32 m0, vcc_lo
	v_lshl_add_u64 v[230:231], s[68:69], 0, v[160:161]
	global_load_lds_dwordx4 v[78:79], off
	v_lshl_add_u64 v[78:79], s[96:97], 0, v[166:167]
	s_add_i32 m0, vcc_lo, 0x2000
	v_lshl_add_u64 v[232:233], s[68:69], 0, v[164:165]
	global_load_lds_dwordx4 v[78:79], off
	s_mov_b32 m0, s74
	s_nop 0
	global_load_lds_dwordx4 v[230:231], off
	s_mov_b32 m0, s75
	s_nop 0
	global_load_lds_dwordx4 v[232:233], off
	s_waitcnt vmcnt(24)
	s_waitcnt lgkmcnt(0)
	s_setprio 1
	s_barrier
	v_mfma_f32_16x16x32_bf16 v[60:63], v[88:91], v[194:197], 0
	v_mfma_f32_16x16x32_bf16 v[60:63], v[108:111], v[198:201], v[60:63]
	v_mfma_f32_16x16x32_bf16 v[56:59], v[128:131], v[194:197], 0
	v_mfma_f32_16x16x32_bf16 v[56:59], v[144:147], v[198:201], v[56:59]
	v_mfma_f32_16x16x32_bf16 v[44:47], v[88:91], v[202:205], 0
	v_mfma_f32_16x16x32_bf16 v[44:47], v[108:111], v[206:209], v[44:47]
	v_mfma_f32_16x16x32_bf16 v[40:43], v[128:131], v[202:205], 0
	v_mfma_f32_16x16x32_bf16 v[40:43], v[144:147], v[206:209], v[40:43]
	v_mfma_f32_16x16x32_bf16 v[28:31], v[88:91], v[210:213], 0
	v_mfma_f32_16x16x32_bf16 v[28:31], v[108:111], v[214:217], v[28:31]
	v_mfma_f32_16x16x32_bf16 v[24:27], v[128:131], v[210:213], 0
	v_mfma_f32_16x16x32_bf16 v[24:27], v[144:147], v[214:217], v[24:27]
	v_mfma_f32_16x16x32_bf16 v[12:15], v[88:91], v[218:221], 0
	v_mfma_f32_16x16x32_bf16 v[12:15], v[108:111], v[222:225], v[12:15]
	v_mfma_f32_16x16x32_bf16 v[8:11], v[128:131], v[218:221], 0
	v_mfma_f32_16x16x32_bf16 v[8:11], v[144:147], v[222:225], v[8:11]
	s_setprio 0
	s_setprio 1
	v_mfma_f32_16x16x32_bf16 v[52:55], v[148:151], v[194:197], 0
	v_mfma_f32_16x16x32_bf16 v[52:55], v[152:155], v[198:201], v[52:55]
	v_mfma_f32_16x16x32_bf16 v[48:51], v[176:179], v[194:197], 0
	v_mfma_f32_16x16x32_bf16 v[48:51], v[190:193], v[198:201], v[48:51]
	v_mfma_f32_16x16x32_bf16 v[36:39], v[148:151], v[202:205], 0
	v_mfma_f32_16x16x32_bf16 v[36:39], v[152:155], v[206:209], v[36:39]
	v_mfma_f32_16x16x32_bf16 v[32:35], v[176:179], v[202:205], 0
	v_mfma_f32_16x16x32_bf16 v[32:35], v[190:193], v[206:209], v[32:35]
	v_mfma_f32_16x16x32_bf16 v[20:23], v[148:151], v[210:213], 0
	v_mfma_f32_16x16x32_bf16 v[20:23], v[152:155], v[214:217], v[20:23]
	v_mfma_f32_16x16x32_bf16 v[16:19], v[176:179], v[210:213], 0
	v_mfma_f32_16x16x32_bf16 v[16:19], v[190:193], v[214:217], v[16:19]
	v_mfma_f32_16x16x32_bf16 v[4:7], v[148:151], v[218:221], 0
	v_mfma_f32_16x16x32_bf16 v[4:7], v[152:155], v[222:225], v[4:7]
	v_mfma_f32_16x16x32_bf16 v[0:3], v[176:179], v[218:221], 0
	v_mfma_f32_16x16x32_bf16 v[0:3], v[190:193], v[222:225], v[0:3]
	s_barrier
	s_setprio 0
	s_add_i32 s96, 0, 0x18000
	v_add_u32_e32 v78, s96, v181
	s_add_i32 s97, 0, 0x1c000
	ds_read_b128 v[88:91], v78
	v_xor_b32_e32 v253, 64, v78
	ds_read_b128 v[108:111], v253
	ds_read_b128 v[128:131], v78 offset:2048
	ds_read_b128 v[144:147], v253 offset:2048
	v_add_u32_e32 v78, s97, v181
	ds_read_b128 v[148:151], v78
	v_xor_b32_e32 v253, 64, v78
	ds_read_b128 v[152:155], v253
	ds_read_b128 v[176:179], v78 offset:2048
	ds_read_b128 v[190:193], v253 offset:2048
	s_add_u32 s68, s68, 0x40000
	s_addc_u32 s69, s69, 0
	s_mov_b32 m0, s76
	v_lshl_add_u64 v[78:79], s[68:69], 0, v[160:161]
	ds_read_b128 v[194:197], v187 offset:32768
	v_xor_b32_e32 v253, 64, v187
	ds_read_b128 v[198:201], v253 offset:32768
	ds_read_b128 v[202:205], v187 offset:34816
	ds_read_b128 v[206:209], v253 offset:34816
	ds_read_b128 v[210:213], v187 offset:36864
	ds_read_b128 v[214:217], v253 offset:36864
	ds_read_b128 v[218:221], v187 offset:38912
	ds_read_b128 v[222:225], v253 offset:38912
	global_load_lds_dwordx4 v[78:79], off
	v_lshl_add_u64 v[78:79], s[68:69], 0, v[164:165]
	s_mov_b32 m0, s77
	s_nop 0
	global_load_lds_dwordx4 v[78:79], off
	s_waitcnt vmcnt(8)
	s_waitcnt lgkmcnt(0)
	s_setprio 1
	s_barrier
	v_mfma_f32_16x16x32_bf16 v[140:143], v[88:91], v[194:197], v[140:143]
	v_mfma_f32_16x16x32_bf16 v[140:143], v[108:111], v[198:201], v[140:143]
	v_mfma_f32_16x16x32_bf16 v[136:139], v[128:131], v[194:197], v[136:139]
	v_mfma_f32_16x16x32_bf16 v[136:139], v[144:147], v[198:201], v[136:139]
	v_mfma_f32_16x16x32_bf16 v[120:123], v[88:91], v[202:205], v[120:123]
	v_mfma_f32_16x16x32_bf16 v[120:123], v[108:111], v[206:209], v[120:123]
	v_mfma_f32_16x16x32_bf16 v[116:119], v[128:131], v[202:205], v[116:119]
	v_mfma_f32_16x16x32_bf16 v[116:119], v[144:147], v[206:209], v[116:119]
	v_mfma_f32_16x16x32_bf16 v[100:103], v[88:91], v[210:213], v[100:103]
	v_mfma_f32_16x16x32_bf16 v[100:103], v[108:111], v[214:217], v[100:103]
	v_mfma_f32_16x16x32_bf16 v[96:99], v[128:131], v[210:213], v[96:99]
	v_mfma_f32_16x16x32_bf16 v[96:99], v[144:147], v[214:217], v[96:99]
	v_mfma_f32_16x16x32_bf16 v[78:81], v[88:91], v[218:221], v[80:83]
	v_mfma_f32_16x16x32_bf16 v[80:83], v[108:111], v[222:225], v[78:81]
	v_mfma_f32_16x16x32_bf16 v[74:77], v[128:131], v[218:221], v[74:77]
	v_mfma_f32_16x16x32_bf16 v[76:79], v[144:147], v[222:225], v[74:77]
	s_setprio 0
	s_setprio 1
	v_mfma_f32_16x16x32_bf16 v[132:135], v[148:151], v[194:197], v[132:135]
	v_mfma_f32_16x16x32_bf16 v[132:135], v[152:155], v[198:201], v[132:135]
	v_mfma_f32_16x16x32_bf16 v[124:127], v[190:193], v[198:201], v[124:127]
	v_mfma_f32_16x16x32_bf16 v[124:127], v[176:179], v[194:197], v[124:127]
	v_mfma_f32_16x16x32_bf16 v[104:107], v[176:179], v[202:205], v[104:107]
	v_mfma_f32_16x16x32_bf16 v[104:107], v[190:193], v[206:209], v[104:107]
	v_mfma_f32_16x16x32_bf16 v[112:115], v[152:155], v[206:209], v[112:115]
	v_mfma_f32_16x16x32_bf16 v[112:115], v[148:151], v[202:205], v[112:115]
	v_mfma_f32_16x16x32_bf16 v[92:95], v[148:151], v[210:213], v[92:95]
	v_mfma_f32_16x16x32_bf16 v[92:95], v[152:155], v[214:217], v[92:95]
	v_mfma_f32_16x16x32_bf16 v[84:87], v[190:193], v[214:217], v[84:87]
	v_mfma_f32_16x16x32_bf16 v[84:87], v[176:179], v[210:213], v[84:87]
	v_mfma_f32_16x16x32_bf16 v[64:67], v[176:179], v[218:221], v[64:67]
	v_mfma_f32_16x16x32_bf16 v[64:67], v[190:193], v[222:225], v[64:67]
	v_mfma_f32_16x16x32_bf16 v[68:71], v[152:155], v[222:225], v[68:71]
	v_mfma_f32_16x16x32_bf16 v[68:71], v[148:151], v[218:221], v[68:71]
	s_barrier
	s_setprio 0
	s_add_i32 s68, s96, s71
	v_lshl_add_u64 v[74:75], v[226:227], 0, s[28:29]
	s_mov_b32 m0, s68
	ds_read_b128 v[194:197], v187 offset:49152
	v_xor_b32_e32 v253, 64, v187
	ds_read_b128 v[198:201], v253 offset:49152
	ds_read_b128 v[202:205], v187 offset:51200
	ds_read_b128 v[206:209], v253 offset:51200
	ds_read_b128 v[210:213], v187 offset:53248
	ds_read_b128 v[214:217], v253 offset:53248
	ds_read_b128 v[218:221], v187 offset:55296
	ds_read_b128 v[222:225], v253 offset:55296
	global_load_lds_dwordx4 v[74:75], off
	s_add_i32 m0, s68, 0x2000
	s_add_u32 s66, s66, 0x40080
	v_lshl_add_u64 v[74:75], v[228:229], 0, s[28:29]
	s_addc_u32 s67, s67, 0
	s_add_i32 s68, s97, s71
	global_load_lds_dwordx4 v[74:75], off
	v_lshl_add_u64 v[74:75], s[66:67], 0, v[162:163]
	s_mov_b32 m0, s68
	s_nop 0
	global_load_lds_dwordx4 v[74:75], off
	v_lshl_add_u64 v[74:75], s[66:67], 0, v[166:167]
	s_add_i32 m0, s68, 0x2000
	s_nop 0
	global_load_lds_dwordx4 v[74:75], off
	v_lshl_add_u64 v[74:75], v[230:231], 0, s[28:29]
	s_mov_b32 m0, s78
	s_nop 0
	global_load_lds_dwordx4 v[74:75], off
	v_lshl_add_u64 v[74:75], v[232:233], 0, s[28:29]
	s_mov_b32 m0, s79
	s_nop 0
	global_load_lds_dwordx4 v[74:75], off
	s_waitcnt vmcnt(8)
	s_waitcnt lgkmcnt(0)
	s_setprio 1
	s_barrier
	v_mfma_f32_16x16x32_bf16 v[60:63], v[88:91], v[194:197], v[60:63]
	v_mfma_f32_16x16x32_bf16 v[60:63], v[108:111], v[198:201], v[60:63]
	v_mfma_f32_16x16x32_bf16 v[56:59], v[144:147], v[198:201], v[56:59]
	v_mfma_f32_16x16x32_bf16 v[56:59], v[128:131], v[194:197], v[56:59]
	v_mfma_f32_16x16x32_bf16 v[40:43], v[128:131], v[202:205], v[40:43]
	v_mfma_f32_16x16x32_bf16 v[40:43], v[144:147], v[206:209], v[40:43]
	v_mfma_f32_16x16x32_bf16 v[44:47], v[108:111], v[206:209], v[44:47]
	v_mfma_f32_16x16x32_bf16 v[44:47], v[88:91], v[202:205], v[44:47]
	v_mfma_f32_16x16x32_bf16 v[28:31], v[88:91], v[210:213], v[28:31]
	v_mfma_f32_16x16x32_bf16 v[28:31], v[108:111], v[214:217], v[28:31]
	v_mfma_f32_16x16x32_bf16 v[24:27], v[144:147], v[214:217], v[24:27]
	v_mfma_f32_16x16x32_bf16 v[24:27], v[128:131], v[210:213], v[24:27]
	v_mfma_f32_16x16x32_bf16 v[8:11], v[128:131], v[218:221], v[8:11]
	v_mfma_f32_16x16x32_bf16 v[8:11], v[144:147], v[222:225], v[8:11]
	v_mfma_f32_16x16x32_bf16 v[12:15], v[108:111], v[222:225], v[12:15]
	v_mfma_f32_16x16x32_bf16 v[12:15], v[88:91], v[218:221], v[12:15]
	s_setprio 0
	s_setprio 1
	v_mfma_f32_16x16x32_bf16 v[52:55], v[148:151], v[194:197], v[52:55]
	v_mfma_f32_16x16x32_bf16 v[52:55], v[152:155], v[198:201], v[52:55]
	v_mfma_f32_16x16x32_bf16 v[48:51], v[190:193], v[198:201], v[48:51]
	v_mfma_f32_16x16x32_bf16 v[48:51], v[176:179], v[194:197], v[48:51]
	v_mfma_f32_16x16x32_bf16 v[32:35], v[176:179], v[202:205], v[32:35]
	v_mfma_f32_16x16x32_bf16 v[32:35], v[190:193], v[206:209], v[32:35]
	v_mfma_f32_16x16x32_bf16 v[36:39], v[152:155], v[206:209], v[36:39]
	v_mfma_f32_16x16x32_bf16 v[36:39], v[148:151], v[202:205], v[36:39]
	v_mfma_f32_16x16x32_bf16 v[20:23], v[148:151], v[210:213], v[20:23]
	v_mfma_f32_16x16x32_bf16 v[20:23], v[152:155], v[214:217], v[20:23]
	v_mfma_f32_16x16x32_bf16 v[16:19], v[190:193], v[214:217], v[16:19]
	v_mfma_f32_16x16x32_bf16 v[16:19], v[176:179], v[210:213], v[16:19]
	v_mfma_f32_16x16x32_bf16 v[0:3], v[176:179], v[218:221], v[0:3]
	v_mfma_f32_16x16x32_bf16 v[0:3], v[190:193], v[222:225], v[0:3]
	v_mfma_f32_16x16x32_bf16 v[4:7], v[152:155], v[222:225], v[4:7]
	v_mfma_f32_16x16x32_bf16 v[4:7], v[148:151], v[218:221], v[4:7]
	s_barrier
	s_setprio 0
	s_add_i32 s95, s95, 2
	s_add_u32 s93, s93, 0x100
	s_addc_u32 s94, s94, 0
	s_add_u32 s14, s14, 0x100
	s_addc_u32 s15, s15, 0
	s_branch .LBB0_256
.Lfa_2:
	v_add_u32_e32 v74, s83, v181
	ds_read_b128 v[88:91], v74
	v_xor_b32_e32 v253, 64, v74
	ds_read_b128 v[108:111], v253
	ds_read_b128 v[128:131], v74 offset:2048
	ds_read_b128 v[144:147], v253 offset:2048
	v_add_u32_e32 v74, s84, v181
	ds_read_b128 v[148:151], v74
	v_xor_b32_e32 v253, 64, v74
	ds_read_b128 v[152:155], v253
	ds_read_b128 v[176:179], v74 offset:2048
	ds_read_b128 v[190:193], v253 offset:2048
	s_add_u32 s68, s14, 0xfffc0080
	s_addc_u32 s69, s15, -1
	s_and_b64 s[66:67], s[66:67], exec
	s_cselect_b32 s69, s3, s69
	s_cselect_b32 s68, s61, s68
	s_cselect_b32 s67, s91, s94
	s_cselect_b32 s66, s92, s93
	v_lshl_add_u64 v[74:75], s[14:15], 0, v[170:171]
	s_add_i32 m0, s74, 0xc000
	ds_read_b128 v[194:197], v187
	v_xor_b32_e32 v253, 64, v187
	ds_read_b128 v[198:201], v253
	ds_read_b128 v[202:205], v187 offset:2048
	ds_read_b128 v[206:209], v253 offset:2048
	ds_read_b128 v[210:213], v187 offset:4096
	ds_read_b128 v[214:217], v253 offset:4096
	ds_read_b128 v[218:221], v187 offset:6144
	ds_read_b128 v[222:225], v253 offset:6144
	global_load_lds_dwordx4 v[74:75], off
	v_lshl_add_u64 v[74:75], s[14:15], 0, v[168:169]
	s_add_i32 m0, s74, 0xe000
	s_nop 0
	global_load_lds_dwordx4 v[74:75], off
	s_waitcnt vmcnt(8)
	s_waitcnt lgkmcnt(0)
	s_setprio 1
	s_barrier
	v_mfma_f32_16x16x32_bf16 v[140:143], v[88:91], v[194:197], 0
	v_mfma_f32_16x16x32_bf16 v[136:139], v[128:131], v[194:197], 0
	v_mfma_f32_16x16x32_bf16 v[120:123], v[88:91], v[202:205], 0
	v_mfma_f32_16x16x32_bf16 v[116:119], v[128:131], v[202:205], 0
	v_mfma_f32_16x16x32_bf16 v[100:103], v[88:91], v[210:213], 0
	v_mfma_f32_16x16x32_bf16 v[96:99], v[128:131], v[210:213], 0
	v_mfma_f32_16x16x32_bf16 v[80:83], v[88:91], v[218:221], 0
	v_mfma_f32_16x16x32_bf16 v[74:77], v[128:131], v[218:221], 0
	v_mfma_f32_16x16x32_bf16 v[140:143], v[108:111], v[198:201], v[140:143]
	v_mfma_f32_16x16x32_bf16 v[136:139], v[144:147], v[198:201], v[136:139]
	v_mfma_f32_16x16x32_bf16 v[120:123], v[108:111], v[206:209], v[120:123]
	v_mfma_f32_16x16x32_bf16 v[116:119], v[144:147], v[206:209], v[116:119]
	v_mfma_f32_16x16x32_bf16 v[100:103], v[108:111], v[214:217], v[100:103]
	v_mfma_f32_16x16x32_bf16 v[96:99], v[144:147], v[214:217], v[96:99]
	v_mfma_f32_16x16x32_bf16 v[80:83], v[108:111], v[222:225], v[80:83]
	v_mfma_f32_16x16x32_bf16 v[74:77], v[144:147], v[222:225], v[74:77]
	s_setprio 0
	s_setprio 1
	v_mfma_f32_16x16x32_bf16 v[132:135], v[148:151], v[194:197], 0
	v_mfma_f32_16x16x32_bf16 v[132:135], v[152:155], v[198:201], v[132:135]
	v_mfma_f32_16x16x32_bf16 v[124:127], v[176:179], v[194:197], 0
	v_mfma_f32_16x16x32_bf16 v[124:127], v[190:193], v[198:201], v[124:127]
	v_mfma_f32_16x16x32_bf16 v[112:115], v[148:151], v[202:205], 0
	v_mfma_f32_16x16x32_bf16 v[112:115], v[152:155], v[206:209], v[112:115]
	v_mfma_f32_16x16x32_bf16 v[104:107], v[176:179], v[202:205], 0
	v_mfma_f32_16x16x32_bf16 v[104:107], v[190:193], v[206:209], v[104:107]
	v_mfma_f32_16x16x32_bf16 v[92:95], v[148:151], v[210:213], 0
	v_mfma_f32_16x16x32_bf16 v[92:95], v[152:155], v[214:217], v[92:95]
	v_mfma_f32_16x16x32_bf16 v[84:87], v[176:179], v[210:213], 0
	v_mfma_f32_16x16x32_bf16 v[84:87], v[190:193], v[214:217], v[84:87]
	v_mfma_f32_16x16x32_bf16 v[68:71], v[148:151], v[218:221], 0
	v_mfma_f32_16x16x32_bf16 v[68:71], v[152:155], v[222:225], v[68:71]
	v_mfma_f32_16x16x32_bf16 v[64:67], v[176:179], v[218:221], 0
	v_mfma_f32_16x16x32_bf16 v[64:67], v[190:193], v[222:225], v[64:67]
	s_barrier
	s_setprio 0
	s_add_i32 s96, s83, s71
	v_lshl_add_u64 v[226:227], s[66:67], 0, v[162:163]
	s_mov_b32 m0, s96
	ds_read_b128 v[194:197], v187 offset:16384
	v_xor_b32_e32 v253, 64, v187
	ds_read_b128 v[198:201], v253 offset:16384
	ds_read_b128 v[202:205], v187 offset:18432
	ds_read_b128 v[206:209], v253 offset:18432
	ds_read_b128 v[210:213], v187 offset:20480
	ds_read_b128 v[214:217], v253 offset:20480
	ds_read_b128 v[218:221], v187 offset:22528
	ds_read_b128 v[222:225], v253 offset:22528
	global_load_lds_dwordx4 v[226:227], off
	s_add_i32 m0, s96, 0x2000
	s_add_u32 s96, s66, 0x40000
	v_lshl_add_u64 v[228:229], s[66:67], 0, v[166:167]
	s_addc_u32 s97, s67, 0
	s_add_i32 vcc_lo, s84, s71
	global_load_lds_dwordx4 v[228:229], off
	v_lshl_add_u64 v[78:79], s[96:97], 0, v[162:163]
	s_mov_b32 m0, vcc_lo
	v_lshl_add_u64 v[230:231], s[68:69], 0, v[160:161]
	global_load_lds_dwordx4 v[78:79], off
	v_lshl_add_u64 v[78:79], s[96:97], 0, v[166:167]
	s_add_i32 m0, vcc_lo, 0x2000
	v_lshl_add_u64 v[232:233], s[68:69], 0, v[164:165]
	global_load_lds_dwordx4 v[78:79], off
	s_mov_b32 m0, s74
	s_nop 0
	global_load_lds_dwordx4 v[230:231], off
	s_mov_b32 m0, s75
	s_nop 0
	global_load_lds_dwordx4 v[232:233], off
	s_waitcnt vmcnt(8)
	s_waitcnt lgkmcnt(0)
	s_setprio 1
	s_barrier
	v_mfma_f32_16x16x32_bf16 v[60:63], v[88:91], v[194:197], 0
	v_mfma_f32_16x16x32_bf16 v[60:63], v[108:111], v[198:201], v[60:63]
	v_mfma_f32_16x16x32_bf16 v[56:59], v[128:131], v[194:197], 0
	v_mfma_f32_16x16x32_bf16 v[56:59], v[144:147], v[198:201], v[56:59]
	v_mfma_f32_16x16x32_bf16 v[44:47], v[88:91], v[202:205], 0
	v_mfma_f32_16x16x32_bf16 v[44:47], v[108:111], v[206:209], v[44:47]
	v_mfma_f32_16x16x32_bf16 v[40:43], v[128:131], v[202:205], 0
	v_mfma_f32_16x16x32_bf16 v[40:43], v[144:147], v[206:209], v[40:43]
	v_mfma_f32_16x16x32_bf16 v[28:31], v[88:91], v[210:213], 0
	v_mfma_f32_16x16x32_bf16 v[28:31], v[108:111], v[214:217], v[28:31]
	v_mfma_f32_16x16x32_bf16 v[24:27], v[128:131], v[210:213], 0
	v_mfma_f32_16x16x32_bf16 v[24:27], v[144:147], v[214:217], v[24:27]
	v_mfma_f32_16x16x32_bf16 v[12:15], v[88:91], v[218:221], 0
	v_mfma_f32_16x16x32_bf16 v[12:15], v[108:111], v[222:225], v[12:15]
	v_mfma_f32_16x16x32_bf16 v[8:11], v[128:131], v[218:221], 0
	v_mfma_f32_16x16x32_bf16 v[8:11], v[144:147], v[222:225], v[8:11]
	s_setprio 0
	s_setprio 1
	v_mfma_f32_16x16x32_bf16 v[52:55], v[148:151], v[194:197], 0
	v_mfma_f32_16x16x32_bf16 v[52:55], v[152:155], v[198:201], v[52:55]
	v_mfma_f32_16x16x32_bf16 v[48:51], v[176:179], v[194:197], 0
	v_mfma_f32_16x16x32_bf16 v[48:51], v[190:193], v[198:201], v[48:51]
	v_mfma_f32_16x16x32_bf16 v[36:39], v[148:151], v[202:205], 0
	v_mfma_f32_16x16x32_bf16 v[36:39], v[152:155], v[206:209], v[36:39]
	v_mfma_f32_16x16x32_bf16 v[32:35], v[176:179], v[202:205], 0
	v_mfma_f32_16x16x32_bf16 v[32:35], v[190:193], v[206:209], v[32:35]
	v_mfma_f32_16x16x32_bf16 v[20:23], v[148:151], v[210:213], 0
	v_mfma_f32_16x16x32_bf16 v[20:23], v[152:155], v[214:217], v[20:23]
	v_mfma_f32_16x16x32_bf16 v[16:19], v[176:179], v[210:213], 0
	v_mfma_f32_16x16x32_bf16 v[16:19], v[190:193], v[214:217], v[16:19]
	v_mfma_f32_16x16x32_bf16 v[4:7], v[148:151], v[218:221], 0
	v_mfma_f32_16x16x32_bf16 v[4:7], v[152:155], v[222:225], v[4:7]
	v_mfma_f32_16x16x32_bf16 v[0:3], v[176:179], v[218:221], 0
	v_mfma_f32_16x16x32_bf16 v[0:3], v[190:193], v[222:225], v[0:3]
	s_barrier
	s_setprio 0
	s_add_i32 s96, 0, 0x18000
	v_add_u32_e32 v78, s96, v181
	s_add_i32 s97, 0, 0x1c000
	ds_read_b128 v[88:91], v78
	v_xor_b32_e32 v253, 64, v78
	ds_read_b128 v[108:111], v253
	ds_read_b128 v[128:131], v78 offset:2048
	ds_read_b128 v[144:147], v253 offset:2048
	v_add_u32_e32 v78, s97, v181
	ds_read_b128 v[148:151], v78
	v_xor_b32_e32 v253, 64, v78
	ds_read_b128 v[152:155], v253
	ds_read_b128 v[176:179], v78 offset:2048
	ds_read_b128 v[190:193], v253 offset:2048
	s_add_u32 s68, s68, 0x40000
	s_addc_u32 s69, s69, 0
	s_mov_b32 m0, s76
	v_lshl_add_u64 v[78:79], s[68:69], 0, v[160:161]
	ds_read_b128 v[194:197], v187 offset:32768
	v_xor_b32_e32 v253, 64, v187
	ds_read_b128 v[198:201], v253 offset:32768
	ds_read_b128 v[202:205], v187 offset:34816
	ds_read_b128 v[206:209], v253 offset:34816
	ds_read_b128 v[210:213], v187 offset:36864
	ds_read_b128 v[214:217], v253 offset:36864
	ds_read_b128 v[218:221], v187 offset:38912
	ds_read_b128 v[222:225], v253 offset:38912
	global_load_lds_dwordx4 v[78:79], off
	v_lshl_add_u64 v[78:79], s[68:69], 0, v[164:165]
	s_mov_b32 m0, s77
	s_nop 0
	global_load_lds_dwordx4 v[78:79], off
	s_waitcnt vmcnt(8)
	s_waitcnt lgkmcnt(0)
	s_setprio 1
	s_barrier
	v_mfma_f32_16x16x32_bf16 v[140:143], v[88:91], v[194:197], v[140:143]
	v_mfma_f32_16x16x32_bf16 v[140:143], v[108:111], v[198:201], v[140:143]
	v_mfma_f32_16x16x32_bf16 v[136:139], v[128:131], v[194:197], v[136:139]
	v_mfma_f32_16x16x32_bf16 v[136:139], v[144:147], v[198:201], v[136:139]
	v_mfma_f32_16x16x32_bf16 v[120:123], v[88:91], v[202:205], v[120:123]
	v_mfma_f32_16x16x32_bf16 v[120:123], v[108:111], v[206:209], v[120:123]
	v_mfma_f32_16x16x32_bf16 v[116:119], v[128:131], v[202:205], v[116:119]
	v_mfma_f32_16x16x32_bf16 v[116:119], v[144:147], v[206:209], v[116:119]
	v_mfma_f32_16x16x32_bf16 v[100:103], v[88:91], v[210:213], v[100:103]
	v_mfma_f32_16x16x32_bf16 v[100:103], v[108:111], v[214:217], v[100:103]
	v_mfma_f32_16x16x32_bf16 v[96:99], v[128:131], v[210:213], v[96:99]
	v_mfma_f32_16x16x32_bf16 v[96:99], v[144:147], v[214:217], v[96:99]
	v_mfma_f32_16x16x32_bf16 v[78:81], v[88:91], v[218:221], v[80:83]
	v_mfma_f32_16x16x32_bf16 v[80:83], v[108:111], v[222:225], v[78:81]
	v_mfma_f32_16x16x32_bf16 v[74:77], v[128:131], v[218:221], v[74:77]
	v_mfma_f32_16x16x32_bf16 v[76:79], v[144:147], v[222:225], v[74:77]
	s_setprio 0
	s_setprio 1
	v_mfma_f32_16x16x32_bf16 v[132:135], v[148:151], v[194:197], v[132:135]
	v_mfma_f32_16x16x32_bf16 v[132:135], v[152:155], v[198:201], v[132:135]
	v_mfma_f32_16x16x32_bf16 v[124:127], v[190:193], v[198:201], v[124:127]
	v_mfma_f32_16x16x32_bf16 v[124:127], v[176:179], v[194:197], v[124:127]
	v_mfma_f32_16x16x32_bf16 v[104:107], v[176:179], v[202:205], v[104:107]
	v_mfma_f32_16x16x32_bf16 v[104:107], v[190:193], v[206:209], v[104:107]
	v_mfma_f32_16x16x32_bf16 v[112:115], v[152:155], v[206:209], v[112:115]
	v_mfma_f32_16x16x32_bf16 v[112:115], v[148:151], v[202:205], v[112:115]
	v_mfma_f32_16x16x32_bf16 v[92:95], v[148:151], v[210:213], v[92:95]
	v_mfma_f32_16x16x32_bf16 v[92:95], v[152:155], v[214:217], v[92:95]
	v_mfma_f32_16x16x32_bf16 v[84:87], v[190:193], v[214:217], v[84:87]
	v_mfma_f32_16x16x32_bf16 v[84:87], v[176:179], v[210:213], v[84:87]
	v_mfma_f32_16x16x32_bf16 v[64:67], v[176:179], v[218:221], v[64:67]
	v_mfma_f32_16x16x32_bf16 v[64:67], v[190:193], v[222:225], v[64:67]
	v_mfma_f32_16x16x32_bf16 v[68:71], v[152:155], v[222:225], v[68:71]
	v_mfma_f32_16x16x32_bf16 v[68:71], v[148:151], v[218:221], v[68:71]
	s_barrier
	s_setprio 0
	s_add_i32 s68, s96, s71
	v_lshl_add_u64 v[74:75], v[226:227], 0, s[28:29]
	s_mov_b32 m0, s68
	ds_read_b128 v[194:197], v187 offset:49152
	v_xor_b32_e32 v253, 64, v187
	ds_read_b128 v[198:201], v253 offset:49152
	ds_read_b128 v[202:205], v187 offset:51200
	ds_read_b128 v[206:209], v253 offset:51200
	ds_read_b128 v[210:213], v187 offset:53248
	ds_read_b128 v[214:217], v253 offset:53248
	ds_read_b128 v[218:221], v187 offset:55296
	ds_read_b128 v[222:225], v253 offset:55296
	global_load_lds_dwordx4 v[74:75], off
	s_add_i32 m0, s68, 0x2000
	s_add_u32 s66, s66, 0x40080
	v_lshl_add_u64 v[74:75], v[228:229], 0, s[28:29]
	s_addc_u32 s67, s67, 0
	s_add_i32 s68, s97, s71
	global_load_lds_dwordx4 v[74:75], off
	v_lshl_add_u64 v[74:75], s[66:67], 0, v[162:163]
	s_mov_b32 m0, s68
	s_nop 0
	global_load_lds_dwordx4 v[74:75], off
	v_lshl_add_u64 v[74:75], s[66:67], 0, v[166:167]
	s_add_i32 m0, s68, 0x2000
	s_nop 0
	global_load_lds_dwordx4 v[74:75], off
	v_lshl_add_u64 v[74:75], v[230:231], 0, s[28:29]
	s_mov_b32 m0, s78
	s_nop 0
	global_load_lds_dwordx4 v[74:75], off
	v_lshl_add_u64 v[74:75], v[232:233], 0, s[28:29]
	s_mov_b32 m0, s79
	s_nop 0
	global_load_lds_dwordx4 v[74:75], off
	s_waitcnt vmcnt(8)
	s_waitcnt lgkmcnt(0)
	s_setprio 1
	s_barrier
	v_mfma_f32_16x16x32_bf16 v[60:63], v[88:91], v[194:197], v[60:63]
	v_mfma_f32_16x16x32_bf16 v[60:63], v[108:111], v[198:201], v[60:63]
	v_mfma_f32_16x16x32_bf16 v[56:59], v[144:147], v[198:201], v[56:59]
	v_mfma_f32_16x16x32_bf16 v[56:59], v[128:131], v[194:197], v[56:59]
	v_mfma_f32_16x16x32_bf16 v[40:43], v[128:131], v[202:205], v[40:43]
	v_mfma_f32_16x16x32_bf16 v[40:43], v[144:147], v[206:209], v[40:43]
	v_mfma_f32_16x16x32_bf16 v[44:47], v[108:111], v[206:209], v[44:47]
	v_mfma_f32_16x16x32_bf16 v[44:47], v[88:91], v[202:205], v[44:47]
	v_mfma_f32_16x16x32_bf16 v[28:31], v[88:91], v[210:213], v[28:31]
	v_mfma_f32_16x16x32_bf16 v[28:31], v[108:111], v[214:217], v[28:31]
	v_mfma_f32_16x16x32_bf16 v[24:27], v[144:147], v[214:217], v[24:27]
	v_mfma_f32_16x16x32_bf16 v[24:27], v[128:131], v[210:213], v[24:27]
	v_mfma_f32_16x16x32_bf16 v[8:11], v[128:131], v[218:221], v[8:11]
	v_mfma_f32_16x16x32_bf16 v[8:11], v[144:147], v[222:225], v[8:11]
	v_mfma_f32_16x16x32_bf16 v[12:15], v[108:111], v[222:225], v[12:15]
	v_mfma_f32_16x16x32_bf16 v[12:15], v[88:91], v[218:221], v[12:15]
	s_setprio 0
	s_setprio 1
	v_mfma_f32_16x16x32_bf16 v[52:55], v[148:151], v[194:197], v[52:55]
	v_mfma_f32_16x16x32_bf16 v[52:55], v[152:155], v[198:201], v[52:55]
	v_mfma_f32_16x16x32_bf16 v[48:51], v[190:193], v[198:201], v[48:51]
	v_mfma_f32_16x16x32_bf16 v[48:51], v[176:179], v[194:197], v[48:51]
	v_mfma_f32_16x16x32_bf16 v[32:35], v[176:179], v[202:205], v[32:35]
	v_mfma_f32_16x16x32_bf16 v[32:35], v[190:193], v[206:209], v[32:35]
	v_mfma_f32_16x16x32_bf16 v[36:39], v[152:155], v[206:209], v[36:39]
	v_mfma_f32_16x16x32_bf16 v[36:39], v[148:151], v[202:205], v[36:39]
	v_mfma_f32_16x16x32_bf16 v[20:23], v[148:151], v[210:213], v[20:23]
	v_mfma_f32_16x16x32_bf16 v[20:23], v[152:155], v[214:217], v[20:23]
	v_mfma_f32_16x16x32_bf16 v[16:19], v[190:193], v[214:217], v[16:19]
	v_mfma_f32_16x16x32_bf16 v[16:19], v[176:179], v[210:213], v[16:19]
	v_mfma_f32_16x16x32_bf16 v[0:3], v[176:179], v[218:221], v[0:3]
	v_mfma_f32_16x16x32_bf16 v[0:3], v[190:193], v[222:225], v[0:3]
	v_mfma_f32_16x16x32_bf16 v[4:7], v[152:155], v[222:225], v[4:7]
	v_mfma_f32_16x16x32_bf16 v[4:7], v[148:151], v[218:221], v[4:7]
	s_barrier
	s_setprio 0
	s_add_i32 s95, s95, 2
	s_add_u32 s93, s93, 0x100
	s_addc_u32 s94, s94, 0
	s_add_u32 s14, s14, 0x100
	s_addc_u32 s15, s15, 0
	s_branch .LBB0_256
.LBB0_255:
	v_add_u32_e32 v74, s83, v181
	ds_read_b128 v[88:91], v74
	v_xor_b32_e32 v253, 64, v74
	ds_read_b128 v[108:111], v253
	ds_read_b128 v[128:131], v74 offset:2048
	ds_read_b128 v[144:147], v253 offset:2048
	v_add_u32_e32 v74, s84, v181
	ds_read_b128 v[148:151], v74
	v_xor_b32_e32 v253, 64, v74
	ds_read_b128 v[152:155], v253
	ds_read_b128 v[176:179], v74 offset:2048
	ds_read_b128 v[190:193], v253 offset:2048
	s_add_u32 s68, s14, 0xfffc0080
	s_addc_u32 s69, s15, -1
	s_and_b64 s[66:67], s[66:67], exec
	s_cselect_b32 s69, s3, s69
	s_cselect_b32 s68, s61, s68
	s_cselect_b32 s67, s91, s94
	s_cselect_b32 s66, s92, s93
	v_lshl_add_u64 v[74:75], s[14:15], 0, v[170:171]
	s_add_i32 m0, s74, 0xc000
	ds_read_b128 v[194:197], v187
	v_xor_b32_e32 v253, 64, v187
	ds_read_b128 v[198:201], v253
	ds_read_b128 v[202:205], v187 offset:2048
	ds_read_b128 v[206:209], v253 offset:2048
	ds_read_b128 v[210:213], v187 offset:4096
	ds_read_b128 v[214:217], v253 offset:4096
	ds_read_b128 v[218:221], v187 offset:6144
	ds_read_b128 v[222:225], v253 offset:6144
	global_load_lds_dwordx4 v[74:75], off
	v_lshl_add_u64 v[74:75], s[14:15], 0, v[168:169]
	s_add_i32 m0, s74, 0xe000
	s_nop 0
	global_load_lds_dwordx4 v[74:75], off
	s_waitcnt vmcnt(8)
	s_waitcnt lgkmcnt(0)
	s_setprio 1
	s_barrier
	v_mfma_f32_16x16x32_bf16 v[140:143], v[88:91], v[194:197], v[140:143]
	v_mfma_f32_16x16x32_bf16 v[140:143], v[108:111], v[198:201], v[140:143]
	v_mfma_f32_16x16x32_bf16 v[136:139], v[128:131], v[194:197], v[136:139]
	v_mfma_f32_16x16x32_bf16 v[136:139], v[144:147], v[198:201], v[136:139]
	v_mfma_f32_16x16x32_bf16 v[120:123], v[88:91], v[202:205], v[120:123]
	v_mfma_f32_16x16x32_bf16 v[120:123], v[108:111], v[206:209], v[120:123]
	v_mfma_f32_16x16x32_bf16 v[116:119], v[128:131], v[202:205], v[116:119]
	v_mfma_f32_16x16x32_bf16 v[116:119], v[144:147], v[206:209], v[116:119]
	v_mfma_f32_16x16x32_bf16 v[100:103], v[88:91], v[210:213], v[100:103]
	v_mfma_f32_16x16x32_bf16 v[100:103], v[108:111], v[214:217], v[100:103]
	v_mfma_f32_16x16x32_bf16 v[96:99], v[128:131], v[210:213], v[96:99]
	v_mfma_f32_16x16x32_bf16 v[96:99], v[144:147], v[214:217], v[96:99]
	v_mfma_f32_16x16x32_bf16 v[80:83], v[88:91], v[218:221], v[80:83]
	v_mfma_f32_16x16x32_bf16 v[80:83], v[108:111], v[222:225], v[80:83]
	v_mfma_f32_16x16x32_bf16 v[74:77], v[128:131], v[218:221], v[76:79]
	v_mfma_f32_16x16x32_bf16 v[74:77], v[144:147], v[222:225], v[74:77]
	s_setprio 0
	s_setprio 1
	v_mfma_f32_16x16x32_bf16 v[132:135], v[148:151], v[194:197], v[132:135]
	v_mfma_f32_16x16x32_bf16 v[132:135], v[152:155], v[198:201], v[132:135]
	v_mfma_f32_16x16x32_bf16 v[124:127], v[190:193], v[198:201], v[124:127]
	v_mfma_f32_16x16x32_bf16 v[124:127], v[176:179], v[194:197], v[124:127]
	v_mfma_f32_16x16x32_bf16 v[104:107], v[176:179], v[202:205], v[104:107]
	v_mfma_f32_16x16x32_bf16 v[104:107], v[190:193], v[206:209], v[104:107]
	v_mfma_f32_16x16x32_bf16 v[112:115], v[152:155], v[206:209], v[112:115]
	v_mfma_f32_16x16x32_bf16 v[112:115], v[148:151], v[202:205], v[112:115]
	v_mfma_f32_16x16x32_bf16 v[92:95], v[148:151], v[210:213], v[92:95]
	v_mfma_f32_16x16x32_bf16 v[92:95], v[152:155], v[214:217], v[92:95]
	v_mfma_f32_16x16x32_bf16 v[84:87], v[190:193], v[214:217], v[84:87]
	v_mfma_f32_16x16x32_bf16 v[84:87], v[176:179], v[210:213], v[84:87]
	v_mfma_f32_16x16x32_bf16 v[64:67], v[176:179], v[218:221], v[64:67]
	v_mfma_f32_16x16x32_bf16 v[64:67], v[190:193], v[222:225], v[64:67]
	v_mfma_f32_16x16x32_bf16 v[68:71], v[152:155], v[222:225], v[68:71]
	v_mfma_f32_16x16x32_bf16 v[68:71], v[148:151], v[218:221], v[68:71]
	s_barrier
	s_setprio 0
	s_add_i32 s96, s83, s71
	v_lshl_add_u64 v[226:227], s[66:67], 0, v[162:163]
	s_mov_b32 m0, s96
	ds_read_b128 v[194:197], v187 offset:16384
	v_xor_b32_e32 v253, 64, v187
	ds_read_b128 v[198:201], v253 offset:16384
	ds_read_b128 v[202:205], v187 offset:18432
	ds_read_b128 v[206:209], v253 offset:18432
	ds_read_b128 v[210:213], v187 offset:20480
	ds_read_b128 v[214:217], v253 offset:20480
	ds_read_b128 v[218:221], v187 offset:22528
	ds_read_b128 v[222:225], v253 offset:22528
	global_load_lds_dwordx4 v[226:227], off
	s_add_i32 m0, s96, 0x2000
	s_add_u32 s96, s66, 0x40000
	v_lshl_add_u64 v[228:229], s[66:67], 0, v[166:167]
	s_addc_u32 s97, s67, 0
	s_add_i32 vcc_lo, s84, s71
	global_load_lds_dwordx4 v[228:229], off
	v_lshl_add_u64 v[78:79], s[96:97], 0, v[162:163]
	s_mov_b32 m0, vcc_lo
	v_lshl_add_u64 v[230:231], s[68:69], 0, v[160:161]
	global_load_lds_dwordx4 v[78:79], off
	v_lshl_add_u64 v[78:79], s[96:97], 0, v[166:167]
	s_add_i32 m0, vcc_lo, 0x2000
	v_lshl_add_u64 v[232:233], s[68:69], 0, v[164:165]
	global_load_lds_dwordx4 v[78:79], off
	s_mov_b32 m0, s74
	s_nop 0
	global_load_lds_dwordx4 v[230:231], off
	s_mov_b32 m0, s75
	s_nop 0
	global_load_lds_dwordx4 v[232:233], off
	s_waitcnt vmcnt(8)
	s_waitcnt lgkmcnt(0)
	s_setprio 1
	s_barrier
	v_mfma_f32_16x16x32_bf16 v[60:63], v[88:91], v[194:197], v[60:63]
	v_mfma_f32_16x16x32_bf16 v[60:63], v[108:111], v[198:201], v[60:63]
	v_mfma_f32_16x16x32_bf16 v[56:59], v[144:147], v[198:201], v[56:59]
	v_mfma_f32_16x16x32_bf16 v[56:59], v[128:131], v[194:197], v[56:59]
	v_mfma_f32_16x16x32_bf16 v[40:43], v[128:131], v[202:205], v[40:43]
	v_mfma_f32_16x16x32_bf16 v[40:43], v[144:147], v[206:209], v[40:43]
	v_mfma_f32_16x16x32_bf16 v[44:47], v[108:111], v[206:209], v[44:47]
	v_mfma_f32_16x16x32_bf16 v[44:47], v[88:91], v[202:205], v[44:47]
	v_mfma_f32_16x16x32_bf16 v[28:31], v[88:91], v[210:213], v[28:31]
	v_mfma_f32_16x16x32_bf16 v[28:31], v[108:111], v[214:217], v[28:31]
	v_mfma_f32_16x16x32_bf16 v[24:27], v[144:147], v[214:217], v[24:27]
	v_mfma_f32_16x16x32_bf16 v[24:27], v[128:131], v[210:213], v[24:27]
	v_mfma_f32_16x16x32_bf16 v[8:11], v[128:131], v[218:221], v[8:11]
	v_mfma_f32_16x16x32_bf16 v[8:11], v[144:147], v[222:225], v[8:11]
	v_mfma_f32_16x16x32_bf16 v[12:15], v[108:111], v[222:225], v[12:15]
	v_mfma_f32_16x16x32_bf16 v[12:15], v[88:91], v[218:221], v[12:15]
	s_setprio 0
	s_setprio 1
	v_mfma_f32_16x16x32_bf16 v[52:55], v[148:151], v[194:197], v[52:55]
	v_mfma_f32_16x16x32_bf16 v[52:55], v[152:155], v[198:201], v[52:55]
	v_mfma_f32_16x16x32_bf16 v[48:51], v[190:193], v[198:201], v[48:51]
	v_mfma_f32_16x16x32_bf16 v[48:51], v[176:179], v[194:197], v[48:51]
	v_mfma_f32_16x16x32_bf16 v[32:35], v[176:179], v[202:205], v[32:35]
	v_mfma_f32_16x16x32_bf16 v[32:35], v[190:193], v[206:209], v[32:35]
	v_mfma_f32_16x16x32_bf16 v[36:39], v[152:155], v[206:209], v[36:39]
	v_mfma_f32_16x16x32_bf16 v[36:39], v[148:151], v[202:205], v[36:39]
	v_mfma_f32_16x16x32_bf16 v[20:23], v[148:151], v[210:213], v[20:23]
	v_mfma_f32_16x16x32_bf16 v[20:23], v[152:155], v[214:217], v[20:23]
	v_mfma_f32_16x16x32_bf16 v[16:19], v[190:193], v[214:217], v[16:19]
	v_mfma_f32_16x16x32_bf16 v[16:19], v[176:179], v[210:213], v[16:19]
	v_mfma_f32_16x16x32_bf16 v[0:3], v[176:179], v[218:221], v[0:3]
	v_mfma_f32_16x16x32_bf16 v[0:3], v[190:193], v[222:225], v[0:3]
	v_mfma_f32_16x16x32_bf16 v[4:7], v[152:155], v[222:225], v[4:7]
	v_mfma_f32_16x16x32_bf16 v[4:7], v[148:151], v[218:221], v[4:7]
	s_barrier
	s_setprio 0
	s_add_i32 s96, 0, 0x18000
	v_add_u32_e32 v78, s96, v181
	s_add_i32 s97, 0, 0x1c000
	ds_read_b128 v[88:91], v78
	v_xor_b32_e32 v253, 64, v78
	ds_read_b128 v[108:111], v253
	ds_read_b128 v[128:131], v78 offset:2048
	ds_read_b128 v[144:147], v253 offset:2048
	v_add_u32_e32 v78, s97, v181
	ds_read_b128 v[148:151], v78
	v_xor_b32_e32 v253, 64, v78
	ds_read_b128 v[152:155], v253
	ds_read_b128 v[176:179], v78 offset:2048
	ds_read_b128 v[190:193], v253 offset:2048
	s_add_u32 s68, s68, 0x40000
	s_addc_u32 s69, s69, 0
	s_mov_b32 m0, s76
	v_lshl_add_u64 v[78:79], s[68:69], 0, v[160:161]
	ds_read_b128 v[194:197], v187 offset:32768
	v_xor_b32_e32 v253, 64, v187
	ds_read_b128 v[198:201], v253 offset:32768
	ds_read_b128 v[202:205], v187 offset:34816
	ds_read_b128 v[206:209], v253 offset:34816
	ds_read_b128 v[210:213], v187 offset:36864
	ds_read_b128 v[214:217], v253 offset:36864
	ds_read_b128 v[218:221], v187 offset:38912
	ds_read_b128 v[222:225], v253 offset:38912
	global_load_lds_dwordx4 v[78:79], off
	v_lshl_add_u64 v[78:79], s[68:69], 0, v[164:165]
	s_mov_b32 m0, s77
	s_nop 0
	global_load_lds_dwordx4 v[78:79], off
	s_waitcnt vmcnt(8)
	s_waitcnt lgkmcnt(0)
	s_setprio 1
	s_barrier
	v_mfma_f32_16x16x32_bf16 v[140:143], v[88:91], v[194:197], v[140:143]
	v_mfma_f32_16x16x32_bf16 v[140:143], v[108:111], v[198:201], v[140:143]
	v_mfma_f32_16x16x32_bf16 v[136:139], v[128:131], v[194:197], v[136:139]
	v_mfma_f32_16x16x32_bf16 v[136:139], v[144:147], v[198:201], v[136:139]
	v_mfma_f32_16x16x32_bf16 v[120:123], v[88:91], v[202:205], v[120:123]
	v_mfma_f32_16x16x32_bf16 v[120:123], v[108:111], v[206:209], v[120:123]
	v_mfma_f32_16x16x32_bf16 v[116:119], v[128:131], v[202:205], v[116:119]
	v_mfma_f32_16x16x32_bf16 v[116:119], v[144:147], v[206:209], v[116:119]
	v_mfma_f32_16x16x32_bf16 v[100:103], v[88:91], v[210:213], v[100:103]
	v_mfma_f32_16x16x32_bf16 v[100:103], v[108:111], v[214:217], v[100:103]
	v_mfma_f32_16x16x32_bf16 v[96:99], v[128:131], v[210:213], v[96:99]
	v_mfma_f32_16x16x32_bf16 v[96:99], v[144:147], v[214:217], v[96:99]
	v_mfma_f32_16x16x32_bf16 v[78:81], v[88:91], v[218:221], v[80:83]
	v_mfma_f32_16x16x32_bf16 v[80:83], v[108:111], v[222:225], v[78:81]
	v_mfma_f32_16x16x32_bf16 v[74:77], v[128:131], v[218:221], v[74:77]
	v_mfma_f32_16x16x32_bf16 v[76:79], v[144:147], v[222:225], v[74:77]
	s_setprio 0
	s_setprio 1
	v_mfma_f32_16x16x32_bf16 v[132:135], v[148:151], v[194:197], v[132:135]
	v_mfma_f32_16x16x32_bf16 v[132:135], v[152:155], v[198:201], v[132:135]
	v_mfma_f32_16x16x32_bf16 v[124:127], v[190:193], v[198:201], v[124:127]
	v_mfma_f32_16x16x32_bf16 v[124:127], v[176:179], v[194:197], v[124:127]
	v_mfma_f32_16x16x32_bf16 v[104:107], v[176:179], v[202:205], v[104:107]
	v_mfma_f32_16x16x32_bf16 v[104:107], v[190:193], v[206:209], v[104:107]
	v_mfma_f32_16x16x32_bf16 v[112:115], v[152:155], v[206:209], v[112:115]
	v_mfma_f32_16x16x32_bf16 v[112:115], v[148:151], v[202:205], v[112:115]
	v_mfma_f32_16x16x32_bf16 v[92:95], v[148:151], v[210:213], v[92:95]
	v_mfma_f32_16x16x32_bf16 v[92:95], v[152:155], v[214:217], v[92:95]
	v_mfma_f32_16x16x32_bf16 v[84:87], v[190:193], v[214:217], v[84:87]
	v_mfma_f32_16x16x32_bf16 v[84:87], v[176:179], v[210:213], v[84:87]
	v_mfma_f32_16x16x32_bf16 v[64:67], v[176:179], v[218:221], v[64:67]
	v_mfma_f32_16x16x32_bf16 v[64:67], v[190:193], v[222:225], v[64:67]
	v_mfma_f32_16x16x32_bf16 v[68:71], v[152:155], v[222:225], v[68:71]
	v_mfma_f32_16x16x32_bf16 v[68:71], v[148:151], v[218:221], v[68:71]
	s_barrier
	s_setprio 0
	s_add_i32 s68, s96, s71
	v_lshl_add_u64 v[74:75], v[226:227], 0, s[28:29]
	s_mov_b32 m0, s68
	ds_read_b128 v[194:197], v187 offset:49152
	v_xor_b32_e32 v253, 64, v187
	ds_read_b128 v[198:201], v253 offset:49152
	ds_read_b128 v[202:205], v187 offset:51200
	ds_read_b128 v[206:209], v253 offset:51200
	ds_read_b128 v[210:213], v187 offset:53248
	ds_read_b128 v[214:217], v253 offset:53248
	ds_read_b128 v[218:221], v187 offset:55296
	ds_read_b128 v[222:225], v253 offset:55296
	global_load_lds_dwordx4 v[74:75], off
	s_add_i32 m0, s68, 0x2000
	s_add_u32 s66, s66, 0x40080
	v_lshl_add_u64 v[74:75], v[228:229], 0, s[28:29]
	s_addc_u32 s67, s67, 0
	s_add_i32 s68, s97, s71
	global_load_lds_dwordx4 v[74:75], off
	v_lshl_add_u64 v[74:75], s[66:67], 0, v[162:163]
	s_mov_b32 m0, s68
	s_nop 0
	global_load_lds_dwordx4 v[74:75], off
	v_lshl_add_u64 v[74:75], s[66:67], 0, v[166:167]
	s_add_i32 m0, s68, 0x2000
	s_nop 0
	global_load_lds_dwordx4 v[74:75], off
	v_lshl_add_u64 v[74:75], v[230:231], 0, s[28:29]
	s_mov_b32 m0, s78
	s_nop 0
	global_load_lds_dwordx4 v[74:75], off
	v_lshl_add_u64 v[74:75], v[232:233], 0, s[28:29]
	s_mov_b32 m0, s79
	s_nop 0
	global_load_lds_dwordx4 v[74:75], off
	s_waitcnt vmcnt(8)
	s_waitcnt lgkmcnt(0)
	s_setprio 1
	s_barrier
	v_mfma_f32_16x16x32_bf16 v[60:63], v[88:91], v[194:197], v[60:63]
	v_mfma_f32_16x16x32_bf16 v[60:63], v[108:111], v[198:201], v[60:63]
	v_mfma_f32_16x16x32_bf16 v[56:59], v[144:147], v[198:201], v[56:59]
	v_mfma_f32_16x16x32_bf16 v[56:59], v[128:131], v[194:197], v[56:59]
	v_mfma_f32_16x16x32_bf16 v[40:43], v[128:131], v[202:205], v[40:43]
	v_mfma_f32_16x16x32_bf16 v[40:43], v[144:147], v[206:209], v[40:43]
	v_mfma_f32_16x16x32_bf16 v[44:47], v[108:111], v[206:209], v[44:47]
	v_mfma_f32_16x16x32_bf16 v[44:47], v[88:91], v[202:205], v[44:47]
	v_mfma_f32_16x16x32_bf16 v[28:31], v[88:91], v[210:213], v[28:31]
	v_mfma_f32_16x16x32_bf16 v[28:31], v[108:111], v[214:217], v[28:31]
	v_mfma_f32_16x16x32_bf16 v[24:27], v[144:147], v[214:217], v[24:27]
	v_mfma_f32_16x16x32_bf16 v[24:27], v[128:131], v[210:213], v[24:27]
	v_mfma_f32_16x16x32_bf16 v[8:11], v[128:131], v[218:221], v[8:11]
	v_mfma_f32_16x16x32_bf16 v[8:11], v[144:147], v[222:225], v[8:11]
	v_mfma_f32_16x16x32_bf16 v[12:15], v[108:111], v[222:225], v[12:15]
	v_mfma_f32_16x16x32_bf16 v[12:15], v[88:91], v[218:221], v[12:15]
	s_setprio 0
	s_setprio 1
	v_mfma_f32_16x16x32_bf16 v[52:55], v[148:151], v[194:197], v[52:55]
	v_mfma_f32_16x16x32_bf16 v[52:55], v[152:155], v[198:201], v[52:55]
	v_mfma_f32_16x16x32_bf16 v[48:51], v[190:193], v[198:201], v[48:51]
	v_mfma_f32_16x16x32_bf16 v[48:51], v[176:179], v[194:197], v[48:51]
	v_mfma_f32_16x16x32_bf16 v[32:35], v[176:179], v[202:205], v[32:35]
	v_mfma_f32_16x16x32_bf16 v[32:35], v[190:193], v[206:209], v[32:35]
	v_mfma_f32_16x16x32_bf16 v[36:39], v[152:155], v[206:209], v[36:39]
	v_mfma_f32_16x16x32_bf16 v[36:39], v[148:151], v[202:205], v[36:39]
	v_mfma_f32_16x16x32_bf16 v[20:23], v[148:151], v[210:213], v[20:23]
	v_mfma_f32_16x16x32_bf16 v[20:23], v[152:155], v[214:217], v[20:23]
	v_mfma_f32_16x16x32_bf16 v[16:19], v[190:193], v[214:217], v[16:19]
	v_mfma_f32_16x16x32_bf16 v[16:19], v[176:179], v[210:213], v[16:19]
	v_mfma_f32_16x16x32_bf16 v[0:3], v[176:179], v[218:221], v[0:3]
	v_mfma_f32_16x16x32_bf16 v[0:3], v[190:193], v[222:225], v[0:3]
	v_mfma_f32_16x16x32_bf16 v[4:7], v[152:155], v[222:225], v[4:7]
	v_mfma_f32_16x16x32_bf16 v[4:7], v[148:151], v[218:221], v[4:7]
	s_barrier
	s_setprio 0
	s_add_i32 s95, s95, 2
	s_add_u32 s93, s93, 0x100
	s_addc_u32 s94, s94, 0
	s_add_u32 s14, s14, 0x100
	s_addc_u32 s15, s15, 0
	s_cmp_gt_u32 s95, 13
	s_cbranch_scc1 .LBB0_258
